# rows phases: per-row loop waits only for the prefetched loads (counted vmcnt), stores stay in flight across rows
# baseline (speedup 1.0000x reference)
; template <bool DO_LN, bool DO_H, bool DO_GATES, bool WRITE_X> ...
;     ...
;         for (int rr = 0; rr < 16; ++rr) {
;             const int row = row0 + rr;
;             f32x4 v[8];
; #pragma unroll
;             for (int i = 0; i < 8; ++i) v[i] = nv[i];
;             if (rr + 1 < 16) {
; #pragma unroll
;                 for (int i = 0; i < 8; ++i) nv[i] = __builtin_nontemporal_load((const f32x4*)(src + (size_t)(row + 1) * DM + lane * 4 + i * 256)); }
.LBB0_172:
	s_or_b64 exec, exec, s[2:3]
	s_add_i32 s21, s21, 1
	s_waitcnt vmcnt(8)
	v_mov_b64_e32 v[62:63], v[2:3]
	v_mov_b64_e32 v[58:59], v[6:7]
	v_mov_b64_e32 v[54:55], v[10:11]
	v_mov_b64_e32 v[50:51], v[14:15]
	s_waitcnt lgkmcnt(0)
	v_mov_b64_e32 v[46:47], v[18:19]
	v_mov_b64_e32 v[42:43], v[22:23]
	v_mov_b64_e32 v[38:39], v[26:27]
	v_mov_b64_e32 v[34:35], v[30:31]
	v_lshl_add_u64 v[70:71], v[70:71], 0, 32
	v_lshl_add_u64 v[72:73], v[72:73], 0, s[14:15]
	s_cmp_eq_u32 s21, 16
	v_mov_b64_e32 v[60:61], v[0:1]
	v_mov_b64_e32 v[56:57], v[4:5]
	v_mov_b64_e32 v[52:53], v[8:9]
	v_mov_b64_e32 v[48:49], v[12:13]
	v_mov_b64_e32 v[44:45], v[16:17]
	v_mov_b64_e32 v[40:41], v[20:21]
	v_mov_b64_e32 v[36:37], v[24:25]
	v_mov_b64_e32 v[32:33], v[28:29]
	s_cbranch_scc1 .LBB0_170

; __device__ __forceinline__ unsigned cvt_pk_bf16(float lo, float hi) { f32x2_t f = {lo, hi}; bf16x2_t v = __builtin_convertvector(f, bf16x2_t); return __builtin_bit_cast(unsigned, v); }
; template <bool DO_LN, bool DO_H, bool DO_GATES, bool WRITE_X> ...
;     ...
;             for (int i = 0; i < 8; ++i) v[i] = nv[i];
;             if (rr + 1 < 16) {
; #pragma unroll
;                 for (int i = 0; i < 8; ++i) nv[i] = __builtin_nontemporal_load((const f32x4*)(src + (size_t)(row + 1) * DM + lane * 4 + i * 256)); }
;     ...
;                 for (int i = 0; i < 8; ++i) v[i] = (v[i] - mu) * rstd;
;                 if (!WRITE_X && lane == 0) { float* st = (float*)(ws + WS_STATS) + (size_t)row * 2; st[0] = mu; st[1] = rstd; }
;             }
;             if (WRITE_X && !DO_H) {
; #pragma unroll
;                 for (int i = 0; i < 8; ++i) __builtin_nontemporal_store(v[i] * PA[i] + PB[i], (f32x4*)(xout + (size_t)row * DM + lane * 4 + i * 256));
;             }
;             if (DO_H) {
;                 float ga[8];
; #pragma unroll
;                 for (int gg = 0; gg < 8; ++gg) ga[gg] = 0.f;
; #pragma unroll
;                 for (int i = 0; i < 8; ++i) { const f32x4 h = v[i] * PA[i] + PB[i];
;                     u32x2 w; w.x = cvt_pk_bf16(h[0], h[1]); w.y = cvt_pk_bf16(h[2], h[3]);
;                     *(u32x2*)(H + (size_t)row * DM + lane * 4 + i * 256) = w;
.LBB0_600:
	s_or_b64 exec, exec, s[2:3]
	v_mov_b32_e32 v15, v164
	v_mov_b32_e32 v11, v165
	v_mov_b32_e32 v164, v16
	v_mov_b32_e32 v165, v162
	v_mov_b32_e32 v162, v17
	v_pk_mul_f32 v[164:165], v[164:165], v[32:33] op_sel_hi:[1,0]
	v_pk_mul_f32 v[14:15], v[14:15], v[32:33] op_sel_hi:[1,0]
	v_pk_mul_f32 v[16:17], v[162:163], v[32:33] op_sel_hi:[1,0]
	v_pk_mul_f32 v[10:11], v[10:11], v[32:33] op_sel_hi:[1,0]
	v_pk_mul_f32 v[8:9], v[8:9], v[32:33] op_sel_hi:[1,0]
	v_pk_mul_f32 v[6:7], v[6:7], v[32:33] op_sel_hi:[1,0]
	v_pk_mul_f32 v[4:5], v[4:5], v[32:33] op_sel_hi:[1,0]
	v_pk_mul_f32 v[2:3], v[2:3], v[32:33] op_sel_hi:[1,0]
	v_pk_mul_f32 v[12:13], v[12:13], v[32:33] op_sel_hi:[1,0]
	v_pk_mul_f32 v[26:27], v[26:27], v[32:33] op_sel_hi:[1,0]
	v_pk_mul_f32 v[24:25], v[24:25], v[32:33] op_sel_hi:[1,0]
	v_pk_mul_f32 v[22:23], v[22:23], v[32:33] op_sel_hi:[1,0]
	v_pk_mul_f32 v[20:21], v[20:21], v[32:33] op_sel_hi:[1,0]
	v_pk_mul_f32 v[18:19], v[18:19], v[32:33] op_sel_hi:[1,0]
	v_pk_mul_f32 v[28:29], v[28:29], v[32:33] op_sel_hi:[1,0]
	v_pk_mul_f32 v[30:31], v[30:31], v[32:33] op_sel_hi:[1,0]
	v_lshl_add_u64 v[32:33], v[158:159], 0, s[16:17]
	v_add_co_u32_e32 v32, vcc, s85, v32
	v_pk_fma_f32 v[4:5], v[116:117], v[4:5], v[120:121]
	v_pk_fma_f32 v[2:3], v[118:119], v[2:3], v[122:123]
	v_addc_co_u32_e32 v33, vcc, 0, v33, vcc
	v_cvt_pk_bf16_f32 v2, v2, v3
	v_cvt_pk_bf16_f32 v3, v4, v5
	global_store_dwordx2 v[32:33], v[2:3], off offset:1536
	v_pk_fma_f32 v[2:3], v[124:125], v[12:13], v[128:129]
	v_pk_fma_f32 v[4:5], v[126:127], v[26:27], v[130:131]
	v_pk_fma_f32 v[162:163], v[92:93], v[164:165], v[96:97]
	v_cvt_pk_bf16_f32 v4, v4, v5
	v_cvt_pk_bf16_f32 v5, v2, v3
	global_store_dwordx2 v[32:33], v[4:5], off offset:2048
	v_pk_fma_f32 v[2:3], v[132:133], v[24:25], v[136:137]
	v_pk_fma_f32 v[4:5], v[134:135], v[22:23], v[138:139]
	v_pk_fma_f32 v[14:15], v[94:95], v[14:15], v[98:99]
	v_cvt_pk_bf16_f32 v4, v4, v5
	v_cvt_pk_bf16_f32 v5, v2, v3
	global_store_dwordx2 v[32:33], v[4:5], off offset:2560
	v_pk_fma_f32 v[2:3], v[140:141], v[20:21], v[144:145]
	v_pk_fma_f32 v[4:5], v[142:143], v[18:19], v[146:147]
	v_cvt_pk_bf16_f32 v14, v14, v15
	v_cvt_pk_bf16_f32 v15, v162, v163
	v_cvt_pk_bf16_f32 v4, v4, v5
	v_cvt_pk_bf16_f32 v5, v2, v3
	global_store_dwordx2 v[32:33], v[14:15], off
	v_pk_fma_f32 v[14:15], v[100:101], v[16:17], v[104:105]
	v_pk_fma_f32 v[10:11], v[102:103], v[10:11], v[106:107]
	v_pk_fma_f32 v[8:9], v[108:109], v[8:9], v[112:113]
	v_pk_fma_f32 v[6:7], v[110:111], v[6:7], v[114:115]
	global_store_dwordx2 v[32:33], v[4:5], off offset:3072
	v_pk_fma_f32 v[2:3], v[148:149], v[28:29], v[152:153]
	v_pk_fma_f32 v[4:5], v[150:151], v[30:31], v[154:155]
	v_cvt_pk_bf16_f32 v10, v10, v11
	v_cvt_pk_bf16_f32 v11, v14, v15
	v_cvt_pk_bf16_f32 v6, v6, v7
	v_cvt_pk_bf16_f32 v7, v8, v9
	v_cvt_pk_bf16_f32 v4, v4, v5
	v_cvt_pk_bf16_f32 v5, v2, v3
	s_add_u32 s16, s16, 0x1000
	global_store_dwordx2 v[32:33], v[10:11], off offset:512
	global_store_dwordx2 v[32:33], v[6:7], off offset:1024
	global_store_dwordx2 v[32:33], v[4:5], off offset:3584
	s_addc_u32 s17, s17, 0
	s_waitcnt vmcnt(8)
	v_mov_b64_e32 v[30:31], v[50:51]
	v_mov_b64_e32 v[18:19], v[54:55]
	v_mov_b64_e32 v[22:23], v[58:59]
	v_mov_b64_e32 v[26:27], v[62:63]
	v_mov_b64_e32 v[2:3], v[34:35]
	v_mov_b64_e32 v[6:7], v[38:39]
	v_mov_b64_e32 v[10:11], v[42:43]
	v_mov_b64_e32 v[14:15], v[46:47]
	v_lshl_add_u64 v[156:157], v[156:157], 0, 8
	v_add_u32_e32 v160, 1, v160
	s_cmp_eq_u32 s16, 0x10000
	v_mov_b64_e32 v[32:33], v[52:53]
	v_mov_b64_e32 v[20:21], v[56:57]
	v_mov_b64_e32 v[24:25], v[60:61]
	v_mov_b64_e32 v[28:29], v[64:65]
	v_mov_b64_e32 v[4:5], v[36:37]
	v_mov_b64_e32 v[8:9], v[40:41]
	v_mov_b64_e32 v[12:13], v[44:45]
	v_mov_b64_e32 v[16:17], v[48:49]
	s_cbranch_scc1 .LBB0_598

; template <bool DO_LN, bool DO_H, bool DO_GATES, bool WRITE_X> ...
;     ...
;                 float s = 0.f;
; #pragma unroll
;                 for (int i = 0; i < 8; ++i) s += (v[i][0] + v[i][1]) + (v[i][2] + v[i][3]);
;                 const float mu = wave_sum(s, lane) * (1.0f / DM);
;                 float q = 0.f;
; #pragma unroll
;                 for (int i = 0; i < 8; ++i) { const f32x4 d = v[i] - mu; q += (d[0] * d[0] + d[1] * d[1]) + (d[2] * d[2] + d[3] * d[3]); }
;                 const float rstd = 1.0f / sqrtf(wave_sum(q, lane) * (1.0f / DM) + LN_EPS);
.LBB0_724:
	v_mov_b32_e32 v164, v118
	v_mov_b32_e32 v165, v126
	v_mov_b32_e32 v166, v119
	v_mov_b32_e32 v167, v127
	v_pk_add_f32 v[164:165], v[164:165], v[166:167]
	v_mov_b32_e32 v166, v120
	v_mov_b32_e32 v167, v128
	v_mov_b32_e32 v168, v121
	v_mov_b32_e32 v169, v129
	v_pk_add_f32 v[166:167], v[166:167], v[168:169]
	v_mov_b32_e32 v168, v114
	v_pk_add_f32 v[164:165], v[164:165], v[166:167]
	v_mov_b32_e32 v166, v115
	v_mov_b32_e32 v167, v116
	v_mov_b32_e32 v169, v117
	v_pk_add_f32 v[166:167], v[166:167], v[168:169]
	v_add_f32_e32 v155, 0, v165
	v_pk_add_f32 v[166:167], v[166:167], v[166:167] op_sel_hi:[0,1]
	v_add_f32_e32 v165, v164, v155
	v_add_f32_e32 v169, v106, v107
	v_add_f32_e32 v171, v108, v109
	v_mov_b32_e32 v168, v122
	v_mov_b32_e32 v170, v123
	v_mov_b32_e32 v166, v124
	v_mov_b32_e32 v164, v125
	v_pk_add_f32 v[168:169], v[168:169], v[170:171]
	v_pk_add_f32 v[164:165], v[166:167], v[164:165]
	v_mov_b32_e32 v166, v111
	v_pk_add_f32 v[164:165], v[168:169], v[164:165]
	v_mov_b32_e32 v167, v112
	v_mov_b32_e32 v168, v110
	v_mov_b32_e32 v169, v113
	v_pk_add_f32 v[166:167], v[166:167], v[168:169]
	v_pk_add_f32 v[164:165], v[164:165], v[164:165] op_sel_hi:[0,1]
	v_pk_add_f32 v[166:167], v[166:167], v[166:167] op_sel_hi:[0,1]
	v_add_f32_e32 v169, v102, v103
	v_add_f32_e32 v171, v104, v105
	v_mov_b32_e32 v168, v98
	v_mov_b32_e32 v170, v99
	v_mov_b32_e32 v166, v100
	v_mov_b32_e32 v164, v101
	v_pk_add_f32 v[168:169], v[168:169], v[170:171]
	v_pk_add_f32 v[164:165], v[166:167], v[164:165]
	v_add_u32_e32 v154, 1, v154
	v_pk_add_f32 v[164:165], v[168:169], v[164:165]
	s_nop 0
	v_add_f32_e32 v155, v164, v165
	ds_bpermute_b32 v164, v158, v155
	s_waitcnt lgkmcnt(0)
	v_add_f32_e32 v155, v155, v164
	ds_bpermute_b32 v164, v159, v155
	s_waitcnt lgkmcnt(0)
	v_add_f32_e32 v155, v155, v164
	ds_bpermute_b32 v164, v160, v155
	s_waitcnt lgkmcnt(0)
	v_add_f32_e32 v155, v155, v164
	ds_bpermute_b32 v164, v161, v155
	s_waitcnt lgkmcnt(0)
	v_add_f32_e32 v155, v155, v164
	ds_bpermute_b32 v164, v162, v155
	s_waitcnt lgkmcnt(0)
	v_add_f32_e32 v155, v155, v164
	ds_bpermute_b32 v164, v163, v155
	s_waitcnt lgkmcnt(0)
	v_add_f32_e32 v155, v155, v164
	v_fmamk_f32 v127, v155, 0xba000000, v127
	v_fmamk_f32 v119, v155, 0xba000000, v119
	v_fmamk_f32 v129, v155, 0xba000000, v129
	v_fmac_f32_e32 v126, 0xba000000, v155
	v_fmamk_f32 v121, v155, 0xba000000, v121
	v_fmac_f32_e32 v118, 0xba000000, v155
	v_mov_b32_e32 v166, v127
	v_mov_b32_e32 v167, v119
	v_fmamk_f32 v128, v155, 0xba000000, v128
	v_fmamk_f32 v120, v155, 0xba000000, v120
	v_mov_b32_e32 v164, v126
	v_mov_b32_e32 v165, v118
	v_pk_mul_f32 v[166:167], v[166:167], v[166:167]
	v_mov_b32_e32 v168, v129
	v_mov_b32_e32 v169, v121
	v_pk_fma_f32 v[164:165], v[164:165], v[164:165], v[166:167]
	v_mov_b32_e32 v166, v128
	v_mov_b32_e32 v167, v120
	v_pk_mul_f32 v[168:169], v[168:169], v[168:169]
	v_fmamk_f32 v115, v155, 0xba000000, v115
	v_pk_fma_f32 v[166:167], v[166:167], v[166:167], v[168:169]
	v_fmamk_f32 v114, v155, 0xba000000, v114
	v_pk_add_f32 v[164:165], v[164:165], v[166:167]
	v_fmamk_f32 v117, v155, 0xba000000, v117
	v_fmac_f32_e32 v116, 0xba000000, v155
	v_pk_add_f32 v[164:165], v[164:165], v[164:165] op_sel_hi:[0,1]
	v_pk_mul_f32 v[166:167], v[116:117], v[116:117]
	v_pk_mul_f32 v[168:169], v[114:115], v[114:115]
	v_fmamk_f32 v106, v155, 0xba000000, v106
	v_pk_mov_b32 v[170:171], v[168:169], v[166:167] op_sel:[1,0]
	v_mov_b32_e32 v169, v167
	v_fmamk_f32 v107, v155, 0xba000000, v107
	v_fmac_f32_e32 v108, 0xba000000, v155
	v_mul_f32_e32 v164, v106, v106
	v_pk_add_f32 v[166:167], v[170:171], v[168:169]
	v_fmamk_f32 v109, v155, 0xba000000, v109
	v_pk_fma_f32 v[168:169], v[106:107], v[106:107], v[164:165] op_sel_hi:[1,1,0]
	v_mul_f32_e32 v164, v108, v108
	v_pk_add_f32 v[166:167], v[166:167], v[166:167] op_sel_hi:[0,1]
	v_pk_fma_f32 v[170:171], v[108:109], v[108:109], v[164:165] op_sel_hi:[1,1,0]
	v_fmamk_f32 v125, v155, 0xba000000, v125
	v_fmamk_f32 v124, v155, 0xba000000, v124
	v_fmamk_f32 v123, v155, 0xba000000, v123
	v_fmac_f32_e32 v122, 0xba000000, v155
	v_mul_f32_e32 v168, v122, v122
	v_mul_f32_e32 v170, v123, v123
	v_mul_f32_e32 v166, v124, v124
	v_mul_f32_e32 v164, v125, v125
	v_pk_add_f32 v[168:169], v[168:169], v[170:171]
	v_pk_add_f32 v[164:165], v[166:167], v[164:165]
	v_fmamk_f32 v111, v155, 0xba000000, v111
	v_pk_add_f32 v[164:165], v[168:169], v[164:165]
	v_fmamk_f32 v110, v155, 0xba000000, v110
	v_fmamk_f32 v113, v155, 0xba000000, v113
	v_fmac_f32_e32 v112, 0xba000000, v155
	v_pk_add_f32 v[164:165], v[164:165], v[164:165] op_sel_hi:[0,1]
	v_pk_mul_f32 v[166:167], v[112:113], v[112:113]
	v_pk_mul_f32 v[168:169], v[110:111], v[110:111]
	v_fmamk_f32 v102, v155, 0xba000000, v102
	v_pk_mov_b32 v[170:171], v[168:169], v[166:167] op_sel:[1,0]
	v_mov_b32_e32 v169, v167
	v_fmamk_f32 v103, v155, 0xba000000, v103
	v_fmac_f32_e32 v104, 0xba000000, v155
	v_mul_f32_e32 v164, v102, v102
	v_pk_add_f32 v[166:167], v[170:171], v[168:169]
	v_fmamk_f32 v105, v155, 0xba000000, v105
	v_pk_fma_f32 v[168:169], v[102:103], v[102:103], v[164:165] op_sel_hi:[1,1,0]
	v_mul_f32_e32 v164, v104, v104
	v_pk_add_f32 v[166:167], v[166:167], v[166:167] op_sel_hi:[0,1]
	v_pk_fma_f32 v[170:171], v[104:105], v[104:105], v[164:165] op_sel_hi:[1,1,0]
	v_fmamk_f32 v101, v155, 0xba000000, v101
	v_fmamk_f32 v100, v155, 0xba000000, v100
	v_fmamk_f32 v99, v155, 0xba000000, v99
	v_fmac_f32_e32 v98, 0xba000000, v155
	v_mul_f32_e32 v168, v98, v98
	v_mul_f32_e32 v170, v99, v99
	v_mul_f32_e32 v166, v100, v100
	v_mul_f32_e32 v164, v101, v101
	v_pk_add_f32 v[168:169], v[168:169], v[170:171]
	v_pk_add_f32 v[164:165], v[166:167], v[164:165]
	s_nop 0
	v_pk_add_f32 v[164:165], v[168:169], v[164:165]
	s_nop 0
	v_add_f32_e32 v155, v164, v165
	ds_bpermute_b32 v164, v158, v155
	s_waitcnt lgkmcnt(0)
; template <bool DO_LN, bool DO_H, bool DO_GATES, bool WRITE_X> ...
;     ...
;             for (int i = 0; i < 8; ++i) v[i] = nv[i];
;             if (rr + 1 < 16) {
; #pragma unroll
;                 for (int i = 0; i < 8; ++i) nv[i] = __builtin_nontemporal_load((const f32x4*)(src + (size_t)(row + 1) * DM + lane * 4 + i * 256)); }
;     ...
;                 const float rstd = 1.0f / sqrtf(wave_sum(q, lane) * (1.0f / DM) + LN_EPS);
; #pragma unroll
;                 for (int i = 0; i < 8; ++i) v[i] = (v[i] - mu) * rstd;
;                 if (!WRITE_X && lane == 0) { float* st = (float*)(ws + WS_STATS) + (size_t)row * 2; st[0] = mu; st[1] = rstd; }
;             }
;             if (WRITE_X && !DO_H) {
; #pragma unroll
;                 for (int i = 0; i < 8; ++i) __builtin_nontemporal_store(v[i] * PA[i] + PB[i], (f32x4*)(xout + (size_t)row * DM + lane * 4 + i * 256));
	v_add_f32_e32 v155, v155, v164
	ds_bpermute_b32 v164, v159, v155
	s_waitcnt lgkmcnt(0)
	v_add_f32_e32 v155, v155, v164
	ds_bpermute_b32 v164, v160, v155
	s_waitcnt lgkmcnt(0)
	v_add_f32_e32 v155, v155, v164
	ds_bpermute_b32 v164, v161, v155
	s_waitcnt lgkmcnt(0)
	v_add_f32_e32 v155, v155, v164
	ds_bpermute_b32 v164, v162, v155
	s_waitcnt lgkmcnt(0)
	v_add_f32_e32 v155, v155, v164
	ds_bpermute_b32 v164, v163, v155
	s_waitcnt lgkmcnt(0)
	v_add_f32_e32 v155, v155, v164
	v_fmamk_f32 v155, v155, 0x3a000000, v238
	v_mul_f32_e32 v164, 0x4f800000, v155
	v_cmp_gt_f32_e32 vcc, s84, v155
	s_nop 1
	v_cndmask_b32_e32 v155, v155, v164, vcc
	v_sqrt_f32_e32 v164, v155
	s_nop 0
	v_add_u32_e32 v165, -1, v164
	v_fma_f32 v166, -v165, v164, v155
	v_cmp_ge_f32_e64 s[0:1], 0, v166
	v_add_u32_e32 v166, 1, v164
	s_nop 0
	v_cndmask_b32_e64 v165, v164, v165, s[0:1]
	v_fma_f32 v164, -v166, v164, v155
	v_cmp_lt_f32_e64 s[0:1], 0, v164
	s_nop 1
	v_cndmask_b32_e64 v164, v165, v166, s[0:1]
	v_mul_f32_e32 v165, 0x37800000, v164
	v_cndmask_b32_e32 v164, v164, v165, vcc
	v_cmp_class_f32_e32 vcc, v155, v239
	s_nop 1
	v_cndmask_b32_e32 v155, v164, v155, vcc
	v_div_scale_f32 v164, s[0:1], v155, v155, 1.0
	v_rcp_f32_e32 v165, v164
	s_nop 0
	v_fma_f32 v166, -v164, v165, 1.0
	v_fmac_f32_e32 v165, v166, v165
	v_div_scale_f32 v166, vcc, 1.0, v155, 1.0
	v_mul_f32_e32 v167, v166, v165
	v_fma_f32 v168, -v164, v167, v166
	v_fmac_f32_e32 v167, v168, v165
	v_fma_f32 v164, -v164, v167, v166
	v_div_fmas_f32 v164, v164, v165, v167
	v_div_fixup_f32 v164, v164, v155, 1.0
	v_pk_mul_f32 v[126:127], v[126:127], v[164:165] op_sel_hi:[1,0]
	v_pk_mul_f32 v[128:129], v[128:129], v[164:165] op_sel_hi:[1,0]
	v_pk_mul_f32 v[118:119], v[118:119], v[164:165] op_sel_hi:[1,0]
	v_pk_mul_f32 v[120:121], v[120:121], v[164:165] op_sel_hi:[1,0]
	v_pk_mul_f32 v[114:115], v[114:115], v[164:165] op_sel_hi:[1,0]
	v_pk_mul_f32 v[116:117], v[116:117], v[164:165] op_sel_hi:[1,0]
	v_pk_mul_f32 v[106:107], v[106:107], v[164:165] op_sel_hi:[1,0]
	v_pk_mul_f32 v[108:109], v[108:109], v[164:165] op_sel_hi:[1,0]
	v_pk_mul_f32 v[122:123], v[122:123], v[164:165] op_sel_hi:[1,0]
	v_pk_mul_f32 v[124:125], v[124:125], v[164:165] op_sel_hi:[1,0]
	v_pk_mul_f32 v[110:111], v[110:111], v[164:165] op_sel_hi:[1,0]
	v_pk_mul_f32 v[112:113], v[112:113], v[164:165] op_sel_hi:[1,0]
	v_pk_mul_f32 v[102:103], v[102:103], v[164:165] op_sel_hi:[1,0]
	v_pk_mul_f32 v[104:105], v[104:105], v[164:165] op_sel_hi:[1,0]
	v_pk_mul_f32 v[166:167], v[98:99], v[164:165] op_sel_hi:[1,0]
	v_pk_mul_f32 v[164:165], v[100:101], v[164:165] op_sel_hi:[1,0]
	v_lshl_add_u64 v[168:169], v[156:157], 0, s[6:7]
	v_pk_fma_f32 v[100:101], v[4:5], v[128:129], v[12:13]
	v_pk_fma_f32 v[98:99], v[2:3], v[126:127], v[10:11]
	global_store_dwordx4 v[168:169], v[98:101], off nt
	s_add_u32 s6, s6, 0x2000
	s_addc_u32 s7, s7, 0
	v_pk_fma_f32 v[100:101], v[8:9], v[120:121], v[16:17]
	v_pk_fma_f32 v[98:99], v[6:7], v[118:119], v[14:15]
	global_store_dwordx4 v[168:169], v[98:101], off offset:1024 nt
	s_waitcnt vmcnt(2)
	v_mov_b64_e32 v[120:121], v[76:77]
	v_mov_b64_e32 v[128:129], v[80:81]
	v_pk_fma_f32 v[100:101], v[20:21], v[116:117], v[28:29]
	v_pk_fma_f32 v[98:99], v[18:19], v[114:115], v[26:27]
	global_store_dwordx4 v[168:169], v[98:101], off offset:2048 nt
	v_mov_b64_e32 v[116:117], v[72:73]
	s_cmp_eq_u32 s6, 0x20000
	v_pk_fma_f32 v[100:101], v[24:25], v[108:109], v[32:33]
	v_pk_fma_f32 v[98:99], v[22:23], v[106:107], v[30:31]
	v_add_co_u32_e32 v106, vcc, s43, v168
	global_store_dwordx4 v[168:169], v[98:101], off offset:3072 nt
	s_nop 0
	v_addc_co_u32_e32 v107, vcc, 0, v169, vcc
	v_pk_fma_f32 v[100:101], v[36:37], v[124:125], v[40:41]
	v_pk_fma_f32 v[98:99], v[34:35], v[122:123], v[38:39]
	global_store_dwordx4 v[106:107], v[98:101], off nt
	v_mov_b64_e32 v[124:125], v[96:97]
	v_mov_b64_e32 v[122:123], v[94:95]
	v_pk_fma_f32 v[100:101], v[44:45], v[112:113], v[48:49]
	v_pk_fma_f32 v[98:99], v[42:43], v[110:111], v[46:47]
	global_store_dwordx4 v[106:107], v[98:101], off offset:1024 nt
	v_mov_b64_e32 v[112:113], v[92:93]
	v_mov_b64_e32 v[110:111], v[90:91]
	v_pk_fma_f32 v[100:101], v[52:53], v[104:105], v[56:57]
	v_pk_fma_f32 v[98:99], v[50:51], v[102:103], v[54:55]
	global_store_dwordx4 v[106:107], v[98:101], off offset:2048 nt
	v_mov_b64_e32 v[104:105], v[88:89]
	v_mov_b64_e32 v[102:103], v[86:87]
	v_pk_fma_f32 v[100:101], v[60:61], v[164:165], v[64:65]
	v_pk_fma_f32 v[98:99], v[58:59], v[166:167], v[62:63]
	global_store_dwordx4 v[106:107], v[98:101], off offset:3072 nt
	v_mov_b64_e32 v[108:109], v[68:69]
	v_mov_b64_e32 v[106:107], v[66:67]
	v_mov_b64_e32 v[100:101], v[84:85]
	v_mov_b64_e32 v[98:99], v[82:83]
	v_mov_b64_e32 v[114:115], v[70:71]
	v_mov_b64_e32 v[118:119], v[74:75]
	v_mov_b64_e32 v[126:127], v[78:79]
	s_cbranch_scc1 .LBB0_722

; template <bool DO_LN, bool DO_H, bool DO_GATES, bool WRITE_X> ...
;     ...
;         for (int rr = 0; rr < 16; ++rr) {
;             const int row = row0 + rr;
;             f32x4 v[8];
; #pragma unroll
;             for (int i = 0; i < 8; ++i) v[i] = nv[i];
;             if (rr + 1 < 16) {
; #pragma unroll
;                 for (int i = 0; i < 8; ++i) nv[i] = __builtin_nontemporal_load((const f32x4*)(src + (size_t)(row + 1) * DM + lane * 4 + i * 256)); }
.LBB0_735:
	s_or_b64 exec, exec, s[2:3]
	s_add_i32 s14, s14, 1
	s_waitcnt vmcnt(8) lgkmcnt(0)
	v_mov_b64_e32 v[36:37], v[20:21]
	v_mov_b64_e32 v[40:41], v[24:25]
	v_mov_b64_e32 v[44:45], v[28:29]
	v_mov_b64_e32 v[48:49], v[32:33]
	v_mov_b64_e32 v[52:53], v[4:5]
	v_mov_b64_e32 v[56:57], v[8:9]
	v_mov_b64_e32 v[60:61], v[12:13]
	v_mov_b64_e32 v[64:65], v[16:17]
	v_lshl_add_u64 v[156:157], v[156:157], 0, 8
	v_lshl_add_u64 v[158:159], v[158:159], 0, 32
	v_lshl_add_u64 v[160:161], v[160:161], 0, s[94:95]
	s_cmp_eq_u32 s14, 16
	v_mov_b64_e32 v[34:35], v[18:19]
	v_mov_b64_e32 v[38:39], v[22:23]
	v_mov_b64_e32 v[42:43], v[26:27]
	v_mov_b64_e32 v[46:47], v[30:31]
	v_mov_b64_e32 v[50:51], v[2:3]
	v_mov_b64_e32 v[54:55], v[6:7]
	v_mov_b64_e32 v[58:59], v[10:11]
	v_mov_b64_e32 v[62:63], v[14:15]
	s_cbranch_scc1 .LBB0_733
